# grid barrier: non-leader blocks wait on the top generation word directly instead of their XCD's generation word (one hop less per barrier, in-loop sites)
# speedup vs baseline: 1.0319x; 1.0106x over previous
; #define LAS __attribute__((address_space(3)))
; __device__ __forceinline__ XcdBarrier xcd_barrier_post(unsigned* bar, volatile LAS unsigned* st) {
;     XcdBarrier b; b.bar = bar; b.x = xb_xcc_id(); b.st = st;
;     if (threadIdx.x == 0) (void)xb_add(&bar[XB_XCNT(b.x)], 1u);
;     return b;
; }
; __device__ __forceinline__ void xcd_barrier_complete(unsigned* bar, unsigned x, unsigned& nloc, unsigned& nx) {
;     const unsigned G = gridDim.x * gridDim.y * gridDim.z;
;     unsigned sum, cnt, mine, sp = 0u;
;     for (;;) {
;         sum = 0u; cnt = 0u; mine = 0u;
; #pragma unroll
;         for (unsigned j = 0; j < 16; ++j) { const unsigned c = xb_ld(&bar[XB_XCNT(j)]); sum += c; cnt += (c > 0u) ? 1u : 0u; mine = (j == x) ? c : mine; }
;         if (sum == G) break;
;         __builtin_amdgcn_s_sleep(1);
;         if ((++sp & 255u) == 0u) { if (xb_ld(&bar[XB_TMO])) break; if (sp > XB_SPIN_CAP) { atomicAdd(&bar[XB_TMO], 1u); break; } }
;     }
;     nloc = mine > 0u ? mine : 1u; nx = cnt > 0u ? cnt : 1u;
; }
; __device__ __forceinline__ void xcd_barrier(const XcdBarrier& b) {
;     asm volatile("s_waitcnt vmcnt(0)" ::: "memory");
;     __syncthreads();
;     if (threadIdx.x == 0) {
;         unsigned* bar = b.bar;
;         __builtin_amdgcn_s_waitcnt(0);
;         unsigned nloc = b.st[0], nx = b.st[1];
;         if (nloc == 0u) { xcd_barrier_complete(bar, b.x, nloc, nx); b.st[0] = nloc; b.st[1] = nx; }
;         const unsigned old = xb_add(&bar[XB_XSUB(b.x)], 1u);
;         const unsigned gen = old / nloc;
;         if (old + 1u == (gen + 1u) * nloc) {
;             __builtin_amdgcn_fence(__ATOMIC_RELEASE, "agent");
;             asm volatile("s_waitcnt vmcnt(0)" ::: "memory");
;             const unsigned og = xb_add(&bar[XB_TOP], 1u);
;             const unsigned tg = og / nx;
;             if (og + 1u == (tg + 1u) * nx) xb_add(&bar[XB_TOPGEN], 1u);
;             else XB_SPIN(xb_ld(&bar[XB_TOPGEN]) == tg, bar);
;             __builtin_amdgcn_fence(__ATOMIC_ACQUIRE, "agent");
;             xb_add(&bar[XB_XGEN(b.x)], 1u);
;             asm volatile("s_waitcnt vmcnt(0)" ::: "memory");
;         } else {
;             XB_SPIN(xb_ld(&bar[XB_XGEN(b.x)]) == gen, bar);
;             __builtin_amdgcn_fence(__ATOMIC_ACQUIRE, "agent");
;             asm volatile("s_waitcnt vmcnt(0)" ::: "memory");
;         }
.LBB0_275:
	s_or_b64 exec, exec, s[4:5]
	s_cmpk_lt_i32 s91, 0x640
	s_cselect_b64 s[4:5], -1, 0
	s_ashr_i32 s78, s91, 31
	s_lshr_b32 s6, s78, 29
	s_add_i32 s6, s91, s6
	s_ashr_i32 s7, s6, 3
	s_and_b32 s6, s6, -8
	s_add_i32 s11, s91, 0xffc0
	s_sub_i32 s13, s91, s6
	s_ashr_i32 s79, s74, 31
	s_add_u32 s82, s72, 0x69200
	s_addc_u32 s83, s73, 0
	s_add_u32 s8, s72, 0x69400
	s_addc_u32 s9, s73, 0
	s_add_u32 s14, s72, 0x69500
	s_addc_u32 s15, s73, 0
	s_add_u32 s34, s72, 0x69600
	s_addc_u32 s35, s73, 0
	s_add_u32 s16, s72, 0x69700
	v_lshl_add_u64 v[0:1], v[0:1], 2, s[0:1]
	s_mov_b64 s[0:1], 0x1400
	s_addc_u32 s17, s73, 0
	v_lshl_add_u64 v[150:151], v[0:1], 0, s[0:1]
	s_mov_b64 s[0:1], 0x6c500
	v_mov_b32_e32 v152, s72
	v_mov_b32_e32 v153, s73
	v_lshl_add_u64 v[152:153], v[152:153], 0, s[0:1]
	s_add_u32 s0, s72, 0x69800
	s_addc_u32 s1, s73, 0
	s_add_u32 s66, s72, 0x69900
	v_writelane_b32 v252, s16, 10
	s_addc_u32 s67, s73, 0
	s_add_u32 s62, s72, 0x69a00
	v_writelane_b32 v252, s17, 11
	v_writelane_b32 v252, s0, 12
	s_addc_u32 s63, s73, 0
	s_mul_i32 s33, s74, 7
	v_writelane_b32 v252, s1, 13
	s_add_u32 s0, s72, 0x69b00
	s_addc_u32 s1, s73, 0
	v_writelane_b32 v252, s0, 14
	s_mov_b64 s[76:77], s[8:9]
	s_movk_i32 s6, 0xc9
	v_writelane_b32 v252, s1, 15
	s_add_u32 s0, s72, 0x69c00
	s_addc_u32 s1, s73, 0
	v_writelane_b32 v252, s0, 16
	v_cvt_f32_u32_e32 v0, s33
	s_mov_b64 s[80:81], s[14:15]
	v_writelane_b32 v252, s1, 17
	s_add_u32 s0, s72, 0x69d00
	s_addc_u32 s1, s73, 0
	v_writelane_b32 v252, s0, 18
	v_rcp_iflag_f32_e32 v0, v0
	v_mov_b32_e32 v1, 0
	v_writelane_b32 v252, s1, 19
	s_add_u32 s0, s72, 0x69e00
	s_addc_u32 s1, s73, 0
	v_writelane_b32 v252, s0, 20
	v_mul_f32_e32 v0, 0x4f7ffffe, v0
	v_cvt_u32_f32_e32 v0, v0
	v_writelane_b32 v252, s1, 21
	s_add_u32 s0, s72, 0x69f00
	s_addc_u32 s1, s73, 0
	v_writelane_b32 v252, s0, 22
	s_mov_b32 s89, 0
	s_nop 0
	v_writelane_b32 v252, s1, 23
	s_add_u32 s0, s72, 0x6a000
	s_addc_u32 s1, s73, 0
	v_writelane_b32 v252, s0, 24
	s_barrier
	s_nop 0
	v_writelane_b32 v252, s1, 25
	s_add_u32 s0, s72, 0x6a100
	s_addc_u32 s1, s73, 0
	v_writelane_b32 v252, s0, 26
	v_cvt_f32_ubyte0_e32 v195, s11
	v_mov_b32_e32 v196, 1
	v_writelane_b32 v252, s1, 27
	s_add_u32 s0, s72, 0x6a200
	s_addc_u32 s1, s73, 0
	v_writelane_b32 v252, s0, 28
	v_mov_b32_e32 v197, 0x358637bd
	v_mov_b32_e32 v198, 0x3ecc95a3
	v_writelane_b32 v252, s1, 29
	s_add_u32 s0, s72, 0x6a300
	s_addc_u32 s1, s73, 0
	v_writelane_b32 v252, s0, 30
	s_cmp_eq_u32 s3, 15
	v_mov_b64_e32 v[154:155], 0x63f
	v_writelane_b32 v252, s1, 31
	s_cselect_b64 s[0:1], -1, 0
	v_writelane_b32 v252, s0, 32
	s_cmp_eq_u32 s3, 14
	v_mbcnt_hi_u32_b32 v199, -1, v12
	v_writelane_b32 v252, s1, 33
	s_cselect_b64 s[0:1], -1, 0
	v_writelane_b32 v252, s0, 34
	s_cmp_eq_u32 s3, 13
	v_mov_b32_e32 v200, 0x7ff
	v_writelane_b32 v252, s1, 35
	s_cselect_b64 s[0:1], -1, 0
	v_writelane_b32 v252, s0, 36
	s_cmp_eq_u32 s3, 12
	v_mov_b32_e32 v201, 0xff
	v_writelane_b32 v252, s1, 37
	s_cselect_b64 s[0:1], -1, 0
	v_writelane_b32 v252, s0, 38
	s_cmp_eq_u32 s3, 11
	v_mov_b32_e32 v202, 0x2200
	v_writelane_b32 v252, s1, 39
	s_cselect_b64 s[0:1], -1, 0
	v_writelane_b32 v252, s0, 40
	s_cmp_eq_u32 s3, 10
	v_mov_b32_e32 v203, 0x7f800000
	v_writelane_b32 v252, s1, 41
	s_cselect_b64 s[0:1], -1, 0
	v_writelane_b32 v252, s0, 42
	s_cmp_eq_u32 s3, 9
	v_mov_b32_e32 v204, 0x7fc00000
	v_writelane_b32 v252, s1, 43
	s_cselect_b64 s[0:1], -1, 0
	v_writelane_b32 v252, s0, 44
	s_cmp_eq_u32 s3, 8
	v_mov_b32_e32 v205, 0xff800000
	v_writelane_b32 v252, s1, 45
	s_cselect_b64 s[0:1], -1, 0
	v_writelane_b32 v252, s0, 46
	s_cmp_eq_u32 s3, 7
	v_mov_b32_e32 v206, 0xc0
	v_writelane_b32 v252, s1, 47
	s_cselect_b64 s[0:1], -1, 0
	v_writelane_b32 v252, s0, 48
	s_cmp_eq_u32 s3, 6
	v_mov_b32_e32 v207, 0x1000
	v_writelane_b32 v252, s1, 49
	s_cselect_b64 s[0:1], -1, 0
	v_writelane_b32 v252, s0, 50
	s_cmp_eq_u32 s3, 5
	v_mov_b32_e32 v208, 2
	v_writelane_b32 v252, s1, 51
	s_cselect_b64 s[0:1], -1, 0
	v_writelane_b32 v252, s0, 52
	s_cmp_eq_u32 s3, 4
	v_mov_b32_e32 v209, 0x600
	v_writelane_b32 v252, s1, 53
	s_cselect_b64 s[0:1], -1, 0
	v_writelane_b32 v252, s0, 54
	s_cmp_eq_u32 s3, 3
	v_mov_b32_e32 v210, 0xffffff00
	v_writelane_b32 v252, s1, 55
	s_cselect_b64 s[0:1], -1, 0
	v_writelane_b32 v252, s0, 56
	s_cmp_eq_u32 s3, 2
	v_mov_b32_e32 v211, 0x4000
	v_writelane_b32 v252, s1, 57
	s_cselect_b64 s[0:1], -1, 0
	v_writelane_b32 v252, s0, 58
	s_cmp_eq_u32 s3, 1
	v_mov_b32_e32 v212, 0x41f00000
	v_writelane_b32 v252, s1, 59
	s_cselect_b64 s[0:1], -1, 0
	v_writelane_b32 v252, s0, 60
	s_cmp_eq_u32 s3, 0
	v_mov_b32_e32 v10, v1
	v_writelane_b32 v252, s1, 61
	s_mul_i32 s0, s75, s74
	s_mul_i32 s68, s0, s68
	s_cselect_b64 s[0:1], -1, 0
	v_writelane_b32 v252, s0, 62
	v_mov_b32_e32 v11, v1
	v_mov_b32_e32 v12, v1
	v_writelane_b32 v252, s1, 63
	s_add_u32 s0, s72, 0x6c400
	s_addc_u32 s1, s73, 0
	v_writelane_b32 v253, s0, 0
	v_mov_b32_e32 v13, v1
	s_movk_i32 s95, 0xff00
	v_writelane_b32 v253, s1, 1
	s_add_u32 s0, s72, 0x6c500
	s_addc_u32 s1, s73, 0
	v_writelane_b32 v253, s0, 2
	s_cmpk_lg_i32 s74, 0x100
	s_movk_i32 s14, 0x90
	v_writelane_b32 v253, s1, 3
	s_cselect_b64 s[0:1], -1, 0
	v_writelane_b32 v253, s0, 4
	s_cmpk_lt_i32 s91, 0xc0
	s_movk_i32 s85, 0x48
	v_writelane_b32 v253, s1, 5
	s_cselect_b64 s[0:1], -1, 0
	s_sub_i32 s10, 0x900, s33
	s_cmpk_eq_i32 s74, 0x100
	v_writelane_b32 v253, s0, 6
	s_cselect_b64 s[36:37], -1, 0
	s_movk_i32 s84, 0x2200
	v_writelane_b32 v253, s1, 7
	s_and_b64 s[0:1], s[36:37], exec
	s_cselect_b32 s0, 0x700, s60
	v_writelane_b32 v253, s0, 8
	s_sub_i32 s0, s54, 64
	v_writelane_b32 v253, s0, 9
	s_lshl_b32 s0, s91, 6
	s_lshl_b32 s75, s74, 6
	s_lshl_b32 s93, s74, 4
; __global__ void __launch_bounds__(512, 2) fwd_kernel(KArgs a) {
;     ...
;             { IDS; const int ncc = wctx ? NCH : 64; const int SP = NGW - NGW / 8, rk = gw - (gw >> 3) - 1, sh = (nKV > SP ? nKV - SP : 0) % SP;
;               const bool stdg = NGW == 2048; if (!stdg || (gw & 7)) for (int t = stdg ? (rk - sh + SP) % SP : gw; t < nPL; t += stdg ? SP : NGW) { const int gi = t & 3, cc = (t >> 2) % ncc, b = (t >> 2) / ncc;
	s_cmp_gt_i32 s91, 31
	v_readlane_b32 s40, v251, 56
	v_writelane_b32 v253, s0, 10
	s_cselect_b64 s[0:1], -1, 0
	s_add_i32 s3, s69, 0xffffff00
	v_readlane_b32 s54, v252, 6
	v_readlane_b32 s55, v252, 7
	s_add_u32 s16, s54, 0x18a0000
	v_writelane_b32 v253, s3, 11
	s_addc_u32 s17, s55, 0
	v_writelane_b32 v253, s16, 12
	s_add_i32 s3, s60, 0xffffff00
	v_readlane_b32 s41, v251, 57
	v_writelane_b32 v253, s17, 13
	v_readlane_b32 s16, v251, 0
	v_readlane_b32 s20, v251, 4
	v_readlane_b32 s17, v251, 1
	v_readlane_b32 s18, v251, 2
	v_readlane_b32 s19, v251, 3
	v_readlane_b32 s21, v251, 5
	v_readlane_b32 s22, v251, 6
	v_readlane_b32 s23, v251, 7
	s_add_u32 s8, s20, 0x400000
	s_addc_u32 s9, s21, 0
	v_readlane_b32 s16, v251, 8
	v_writelane_b32 v253, s8, 14
	v_readlane_b32 s20, v251, 12
	v_readlane_b32 s21, v251, 13
	v_writelane_b32 v253, s9, 15
	s_add_u32 s8, s20, 0x60000
	s_addc_u32 s9, s21, 0
	v_readlane_b32 s22, v251, 14
	v_writelane_b32 v253, s8, 16
	v_readlane_b32 s17, v251, 9
	v_readlane_b32 s18, v251, 10
	v_readlane_b32 s19, v251, 11
	v_readlane_b32 s23, v251, 15
	v_readlane_b32 s24, v251, 16
	v_readlane_b32 s25, v251, 17
	v_readlane_b32 s26, v251, 18
	v_readlane_b32 s27, v251, 19
	v_readlane_b32 s28, v251, 20
	v_readlane_b32 s29, v251, 21
	v_readlane_b32 s30, v251, 22
	v_readlane_b32 s31, v251, 23
	v_writelane_b32 v253, s9, 17
	s_add_u32 s8, s22, 0x40000
	s_addc_u32 s9, s23, 0
	v_readlane_b32 s16, v251, 24
	v_readlane_b32 s17, v251, 25
	v_readlane_b32 s18, v251, 26
	v_readlane_b32 s19, v251, 27
	v_readlane_b32 s28, v251, 36
	v_readlane_b32 s29, v251, 37
	v_writelane_b32 v253, s8, 18
	v_readlane_b32 s30, v251, 38
	v_readlane_b32 s31, v251, 39
	s_mov_b64 s[16:17], s[28:29]
	v_writelane_b32 v253, s9, 19
	s_add_u32 s8, s16, 0x40000
	s_addc_u32 s9, s17, 0
	s_cmp_lt_i32 s13, 0
	s_cselect_b32 s6, s6, 0xc8
	v_writelane_b32 v253, s8, 20
	s_mul_i32 s6, s13, s6
	s_add_i32 s6, s6, s7
	v_writelane_b32 v253, s9, 21
	v_writelane_b32 v253, s7, 22
	s_mul_hi_i32 s7, s6, 0x51eb851f
	s_lshr_b32 s8, s7, 31
	s_ashr_i32 s7, s7, 4
	s_add_i32 s7, s7, s8
	s_mul_i32 s8, s7, 50
	s_sub_i32 s6, s6, s8
	s_bfe_u32 s8, s6, 0x10007
	s_add_i32 s8, s6, s8
	s_and_b32 s9, s8, 0xfe
	s_sub_i32 s6, s6, s9
	s_lshl_b32 s7, s7, 1
	s_sext_i32_i8 s6, s6
	s_add_i32 s6, s7, s6
	v_writelane_b32 v253, s6, 23
	s_sub_i32 s6, 0, s33
	v_readfirstlane_b32 s7, v0
	s_mul_i32 s6, s6, s7
	s_mul_hi_u32 s6, s7, s6
	s_add_i32 s7, s7, s6
	s_mul_hi_u32 s6, s10, s7
	s_mul_i32 s6, s6, s33
	s_sub_i32 s9, s10, s6
	s_bfe_i32 s6, s8, 0x80000
	s_sext_i32_i16 s6, s6
	s_ashr_i32 s6, s6, 1
	v_writelane_b32 v253, s6, 24
	v_writelane_b32 v253, s36, 25
	s_and_b64 s[6:7], s[0:1], s[36:37]
	s_lshr_b32 s0, s13, 31
	v_writelane_b32 v253, s37, 26
	v_writelane_b32 v253, s13, 27
	v_writelane_b32 v253, s0, 28
	s_sub_i32 s0, s9, s33
	s_cmp_ge_u32 s9, s33
	s_cselect_b32 s0, s0, s9
	s_sub_i32 s1, s0, s33
	s_cmp_ge_u32 s0, s33
	s_cselect_b32 s0, s1, s0
	v_writelane_b32 v253, s0, 29
	s_abs_i32 s0, s33
	v_cvt_f32_u32_e32 v0, s0
	v_writelane_b32 v253, s33, 30
	v_writelane_b32 v253, s0, 31
	s_sub_i32 s0, 0, s0
	v_rcp_iflag_f32_e32 v0, v0
	s_ashr_i32 s61, s60, 31
	v_readlane_b32 s42, v251, 58
	v_readlane_b32 s43, v251, 59
	v_mul_f32_e32 v0, 0x4f7ffffe, v0
	v_cvt_u32_f32_e32 v0, v0
	v_readlane_b32 s44, v251, 60
	v_readlane_b32 s45, v251, 61
	v_readlane_b32 s46, v251, 62
	v_readfirstlane_b32 s1, v0
	s_mul_i32 s0, s0, s1
	s_mul_hi_u32 s0, s1, s0
	s_add_i32 s0, s1, s0
	v_writelane_b32 v253, s0, 32
	s_mul_i32 s0, s91, 48
	v_writelane_b32 v253, s11, 33
	s_add_i32 s0, s0, 35
	v_writelane_b32 v253, s0, 34
	s_add_i32 s0, s12, 0xfffe0000
	v_writelane_b32 v253, s0, 35
	s_xor_b64 s[0:1], s[6:7], -1
	v_writelane_b32 v253, s0, 36
	v_readlane_b32 s47, v251, 63
	v_readlane_b32 s48, v252, 0
	v_writelane_b32 v253, s1, 37
	s_xor_b64 s[0:1], s[4:5], -1
	v_writelane_b32 v253, s0, 38
	s_lshl_b64 s[4:5], s[60:61], 11
	v_readlane_b32 s49, v252, 1
	v_writelane_b32 v253, s1, 39
	s_mov_b32 s0, s74
	v_writelane_b32 v253, s0, 40
	s_lshl_b32 s0, s91, 7
	v_writelane_b32 v253, s0, 41
	s_lshl_b32 s0, s74, 7
	v_writelane_b32 v253, s0, 42
	s_ashr_i32 s0, s69, 31
	v_writelane_b32 v253, s0, 43
	s_add_i32 s1, 0, 0x20020
	v_writelane_b32 v253, s1, 44
	s_add_i32 s1, 0, 0x20024
	v_writelane_b32 v253, s1, 45
	s_add_i32 s1, 0, 0x2600
	v_writelane_b32 v253, s1, 46
	v_writelane_b32 v253, s4, 47
	v_readlane_b32 s50, v252, 2
	v_readlane_b32 s51, v252, 3
	v_writelane_b32 v253, s5, 48
	s_mov_b64 s[4:5], 0
	v_writelane_b32 v253, s4, 49
	v_readlane_b32 s52, v252, 4
	v_readlane_b32 s53, v252, 5
	v_writelane_b32 v253, s5, 50
	s_mov_b32 s4, s60
	v_writelane_b32 v253, s4, 51
	v_readlane_b32 s20, v251, 28
	v_readlane_b32 s21, v251, 29
	v_writelane_b32 v253, s5, 52
	v_writelane_b32 v253, s34, 53
	v_readlane_b32 s22, v251, 30
	v_readlane_b32 s23, v251, 31
	v_writelane_b32 v253, s35, 54
	v_writelane_b32 v253, s66, 55
	v_readlane_b32 s24, v251, 32
	v_readlane_b32 s25, v251, 33
	v_writelane_b32 v253, s67, 56
	v_writelane_b32 v253, s62, 57
	v_readlane_b32 s26, v251, 34
	v_readlane_b32 s27, v251, 35
	v_writelane_b32 v253, s63, 58
	v_writelane_b32 v253, s72, 59
	s_mov_b64 s[18:19], s[30:31]
	s_movk_i32 s9, 0x900
	v_writelane_b32 v253, s73, 60
	v_writelane_b32 v253, s74, 61
	v_writelane_b32 v253, s75, 62
	v_writelane_b32 v253, s96, 63
	s_movk_i32 s33, 0x2000
	s_movk_i32 s0, 0x4000
	v_writelane_b32 v254, s97, 0
	v_writelane_b32 v254, s91, 1
	v_writelane_b32 v254, s78, 2
	v_writelane_b32 v254, s79, 3
	v_writelane_b32 v254, s82, 4
	s_movk_i32 s90, 0x1000
	s_mov_b32 s94, 0x38e38e39
	v_writelane_b32 v254, s83, 5
	v_writelane_b32 v254, s76, 6
	s_mov_b32 s70, 0x3f2aaaab
	s_mov_b32 s71, 0x3f317218
	v_writelane_b32 v254, s77, 7
	v_writelane_b32 v254, s80, 8
	s_mov_b32 s12, 0x7f800000
	s_mov_b32 s13, 0x33800000
	v_writelane_b32 v254, s81, 9
	v_writelane_b32 v254, s68, 10
	v_writelane_b32 v254, s75, 11
	v_writelane_b32 v254, s93, 12
	s_mov_b32 s92, 0xc1f00000
	s_mov_b64 s[6:7], -1
	s_mov_b64 s[86:87], 0x80
	s_mov_b64 s[64:65], 0x100
	s_mov_b32 s8, 0x3e16c73f
	s_mov_b64 s[10:11], 0xc000
	s_mov_b64 s[16:17], 0x20000
	s_mov_b32 s2, s89
	v_writelane_b32 v254, s69, 13
	s_branch .LBB0_277

; #define WSL unsigned char* wsl = a.ws; asm volatile("" : "+s"(wsl))
; #define GSYNC() xcd_barrier(xbar)
; __global__ void __launch_bounds__(512, 2) fwd_kernel(KArgs a) {
;     ...
;     for (int l = 0; l < 2; ++l) {
;         for (int hf = 0; hf < 2; ++hf) {
;             const bool wctx = (l == 0);
;             for (int rep_ = 0; rep_ < REP_B; ++rep_) {
;     ...
;             {
;                 WSL; pg8::Gemm g{HZ, WIN + (size_t)l * NPAD * 1024, 1024, 0, 0};
;                 pg8::Sched S{64, 25, 8, wctx ? 25 : 3, 1, G, bid};
;                 pg8::EpiP E{P, INP};
;                 pg8::gemm_phase<pg8::EpiP>(lds, g, S, E);
;             }
;     ...
;             }
;             GSYNC();
;             for (int rep_ = 0; rep_ < REP_C; ++rep_) {
;     ...
;             const int nQP = (wctx ? MH : ML) / 8, nKV = MH / 8, nLR = HB * NCH * 4, nPL = wctx ? HB * NCH * 4 : HB * 64 * 4;
.Lpost_getpc1:
	s_add_u32 s98, s98, (.LBB0_1640-.Lpost_getpc1)&4294967295
	s_addc_u32 s99, s99, (.LBB0_1640-.Lpost_getpc1)>>32
	s_setpc_b64 s[98:99]
	s_branch .Lmy_pad_LBB0277
	s_nop 0
	s_nop 0
	s_nop 0
	s_nop 0
	s_nop 0
	s_nop 0
	s_nop 0
	s_nop 0
	s_nop 0
	s_nop 0
	s_nop 0
	s_nop 0
	s_nop 0
.Lmy_pad_LBB0277:
.LBB0_277:
	v_writelane_b32 v254, s2, 14
	s_xor_b64 s[4:5], s[6:7], -1
	s_mov_b64 s[52:53], s[6:7]
	v_writelane_b32 v254, s3, 15
	v_writelane_b32 v254, s4, 16
	s_mov_b32 s15, s89
	v_readlane_b32 s36, v251, 8
	v_writelane_b32 v254, s5, 17
	s_and_b64 s[4:5], s[6:7], exec
	s_cselect_b32 s54, 25, 3
	s_lshl_b32 s1, s54, 3
	s_add_i32 s56, s1, 0x640
	s_cmp_lt_i32 s91, s56
	s_cselect_b64 s[4:5], -1, 0
	s_and_b64 s[6:7], s[6:7], exec
	s_cselect_b32 s24, s14, 0x80
	s_movk_i32 s1, 0x800
	s_cselect_b32 s1, 0x900, s1
	s_cmp_lt_i32 s91, s24
	v_writelane_b32 v254, s1, 18
	s_cselect_b64 s[6:7], -1, 0
	v_writelane_b32 v254, s6, 19
	s_cmp_ge_i32 s91, s24
	v_readlane_b32 s37, v251, 9
	v_writelane_b32 v254, s7, 20
	s_cselect_b64 s[6:7], -1, 0
	s_lshl_b32 s14, s2, 8
	s_mov_b32 s2, s14
	s_lshl_b64 s[18:19], s[14:15], 2
	v_writelane_b32 v254, s2, 21
	s_add_u32 s14, s36, s18
	s_addc_u32 s15, s37, s19
	v_writelane_b32 v254, s3, 22
	v_writelane_b32 v254, s14, 23
	s_mov_b32 s21, s89
	v_readlane_b32 s44, v251, 16
	v_writelane_b32 v254, s15, 24
	v_readlane_b32 s45, v251, 17
	v_readlane_b32 s14, v254, 14
	s_mul_i32 s20, s14, 0x60
	s_lshl_b64 s[20:21], s[20:21], 2
	v_readlane_b32 s15, v254, 15
	s_add_u32 s14, s44, s20
	s_addc_u32 s15, s45, s21
	v_writelane_b32 v254, s14, 25
	s_mov_b32 s23, s89
	v_readlane_b32 s38, v251, 10
	v_writelane_b32 v254, s15, 26
	v_readlane_b32 s39, v251, 11
	v_readlane_b32 s14, v254, 14
	s_lshl_b32 s22, s14, 7
	s_lshl_b64 s[22:23], s[22:23], 2
	v_readlane_b32 s15, v254, 15
	s_add_u32 s14, s38, s22
	s_addc_u32 s15, s39, s23
	v_writelane_b32 v254, s14, 27
	v_readlane_b32 s46, v251, 18
	v_readlane_b32 s47, v251, 19
	v_writelane_b32 v254, s15, 28
	v_readlane_b32 s40, v251, 12
	v_readlane_b32 s14, v254, 14
	s_lshl_b32 s1, s14, 9
	v_readlane_b32 s15, v254, 15
	s_add_u32 s14, s46, s20
	v_writelane_b32 v254, s1, 29
	s_addc_u32 s15, s47, s21
	v_writelane_b32 v254, s14, 30
	v_readlane_b32 s41, v251, 13
	v_readlane_b32 s42, v251, 14
	v_writelane_b32 v254, s15, 31
	v_readlane_b32 s43, v251, 15
	v_readlane_b32 s14, v254, 14
	s_lshl_b32 s1, s14, 10
	v_readlane_b32 s15, v254, 15
	v_writelane_b32 v254, s1, 32
	s_or_b32 s1, s24, 32
	v_readlane_b32 s14, v254, 14
	s_lshl_b32 s2, s14, 1
	v_readlane_b32 s15, v254, 15
	s_cmp_le_i32 s74, s1
	s_cselect_b64 s[14:15], -1, 0
	v_writelane_b32 v254, s14, 33
	v_readlane_b32 s48, v251, 20
	v_readlane_b32 s49, v251, 21
	v_writelane_b32 v254, s15, 34
	v_readlane_b32 s50, v251, 22
	v_readlane_b32 s14, v254, 14
	s_lshl_b32 s1, s14, 4
	v_readlane_b32 s15, v254, 15
	v_writelane_b32 v254, s1, 35
	s_sub_i32 s1, s91, s24
	v_readlane_b32 s51, v251, 23
	s_cmpk_lt_i32 s1, 0xc0
	v_writelane_b32 v254, s1, 36
	s_cselect_b64 s[20:21], -1, 0
	s_sub_i32 s1, s74, s24
	v_readlane_b32 s36, v251, 40
	s_and_b64 s[22:23], s[52:53], exec
	v_readlane_b32 s50, v251, 54
	v_writelane_b32 v254, s24, 37
	s_cselect_b32 s55, 0x48, 64
	v_readlane_b32 s51, v251, 55
	s_add_u32 s14, s50, s18
	v_writelane_b32 v254, s1, 38
	s_addc_u32 s15, s51, s19
	v_writelane_b32 v254, s14, 39
	v_readlane_b32 s24, v251, 0
	v_readlane_b32 s25, v251, 1
	v_writelane_b32 v254, s15, 40
	s_add_u32 s14, s24, s18
	s_addc_u32 s15, s25, s19
	v_writelane_b32 v254, s14, 41
	v_readlane_b32 s37, v251, 41
	v_readlane_b32 s38, v251, 42
	v_writelane_b32 v254, s15, 42
	v_readlane_b32 s39, v251, 43
	v_readlane_b32 s14, v254, 14
	s_lshl_b32 s1, s14, 5
	v_readlane_b32 s15, v254, 15
	v_writelane_b32 v254, s1, 43
	s_and_b64 s[22:23], s[52:53], exec
	s_movk_i32 s1, 0x120
	v_readlane_b32 s40, v251, 44
	v_readlane_b32 s41, v251, 45
	v_readlane_b32 s42, v251, 46
	v_readlane_b32 s43, v251, 47
	v_readlane_b32 s44, v251, 48
	v_readlane_b32 s45, v251, 49
	v_readlane_b32 s46, v251, 50
	v_readlane_b32 s47, v251, 51
	v_readlane_b32 s48, v251, 52
	v_readlane_b32 s49, v251, 53
	s_cselect_b32 s1, s1, 0x100
	s_cmp_lt_i32 s91, s1
	v_readlane_b32 s36, v251, 24
	v_writelane_b32 v254, s1, 44
	s_cselect_b64 s[14:15], -1, 0
	v_readlane_b32 s46, v251, 34
	v_readlane_b32 s47, v251, 35
	v_writelane_b32 v254, s14, 45
	s_lshl_b32 s1, s55, 5
	s_mov_b64 s[22:23], s[46:47]
	v_writelane_b32 v254, s15, 46
	s_add_u32 s14, s22, s18
	v_writelane_b32 v254, s1, 47
	s_addc_u32 s15, s23, s19
	v_writelane_b32 v254, s14, 48
	s_lshl_b32 s24, s55, 2
	v_readlane_b32 s37, v251, 25
	v_writelane_b32 v254, s15, 49
	v_readlane_b32 s38, v251, 26
	v_readlane_b32 s14, v254, 14
	v_readlane_b32 s15, v254, 15
	s_lshl_b32 s1, s14, 20
	v_readlane_b32 s14, v254, 14
	v_readlane_b32 s15, v254, 15
	s_mov_b32 s15, s89
	s_cmp_lt_i32 s91, s24
	v_writelane_b32 v254, s14, 14
	v_readlane_b32 s39, v251, 27
	v_readlane_b32 s40, v251, 28
	v_writelane_b32 v254, s15, 15
	s_cselect_b64 s[14:15], -1, 0
; __device__ __forceinline__ unsigned xb_ld(unsigned* p)              { return __hip_atomic_load(p, __ATOMIC_RELAXED, __HIP_MEMORY_SCOPE_AGENT); }
; __device__ __forceinline__ unsigned xb_add(unsigned* p, unsigned v) { return __hip_atomic_fetch_add(p, v, __ATOMIC_RELAXED, __HIP_MEMORY_SCOPE_AGENT); }
; #define XB_SPIN(cond, bar) do { unsigned _sp = 0; while (cond) { __builtin_amdgcn_s_sleep(1); \
;     if ((++_sp & 255u) == 0u) { if (xb_ld(&(bar)[XB_TMO])) break; if (_sp > XB_SPIN_CAP) { atomicAdd(&(bar)[XB_TMO], 1u); break; } } } } while (0)
; #define WSL unsigned char* wsl = a.ws; asm volatile("" : "+s"(wsl))
; #define GSYNC() xcd_barrier(xbar)
; __device__ __forceinline__ void xcd_barrier(const XcdBarrier& b) {
;     ...
;             __builtin_amdgcn_fence(__ATOMIC_RELEASE, "agent");
;             asm volatile("s_waitcnt vmcnt(0)" ::: "memory");
;             const unsigned og = xb_add(&bar[XB_TOP], 1u);
;             const unsigned tg = og / nx;
;             if (og + 1u == (tg + 1u) * nx) xb_add(&bar[XB_TOPGEN], 1u);
;             else XB_SPIN(xb_ld(&bar[XB_TOPGEN]) == tg, bar);
;             __builtin_amdgcn_fence(__ATOMIC_ACQUIRE, "agent");
;             xb_add(&bar[XB_XGEN(b.x)], 1u);
;             asm volatile("s_waitcnt vmcnt(0)" ::: "memory");
; __global__ void __launch_bounds__(512, 2) fwd_kernel(KArgs a) {
;     ...
;                 WSL; pg8::Gemm g{HZ, WIN + (size_t)l * NPAD * 1024, 1024, 0, 0};
;                 pg8::Sched S{64, 25, 8, wctx ? 25 : 3, 1, G, bid};
;                 pg8::EpiP E{P, INP};
;                 pg8::gemm_phase<pg8::EpiP>(lds, g, S, E);
;             }
;     ...
;             }
;             GSYNC();
;             for (int rep_ = 0; rep_ < REP_C; ++rep_) {
;     ...
;             const int nQP = (wctx ? MH : ML) / 8, nKV = MH / 8, nLR = HB * NCH * 4, nPL = wctx ? HB * NCH * 4 : HB * 64 * 4;
	v_writelane_b32 v254, s14, 50
	s_lshr_b32 s25, s55, 1
	v_readlane_b32 s41, v251, 29
	v_writelane_b32 v254, s15, 51
	s_or_b32 s14, s25, 1
	v_writelane_b32 v254, s14, 52
	v_readlane_b32 s42, v251, 30
	v_readlane_b32 s14, v254, 14
	v_readlane_b32 s15, v254, 15
	s_lshl_b64 s[14:15], s[14:15], 21
	v_writelane_b32 v254, s14, 53
	v_readlane_b32 s43, v251, 31
	v_readlane_b32 s44, v251, 32
	v_readlane_b32 s45, v251, 33
	v_readlane_b32 s48, v251, 36
	v_readlane_b32 s49, v251, 37
	v_readlane_b32 s50, v251, 38
	v_readlane_b32 s51, v251, 39
	v_writelane_b32 v254, s15, 54
	v_writelane_b32 v254, s52, 55
	v_readlane_b32 s36, v251, 56
	v_readlane_b32 s31, v251, 7
	v_writelane_b32 v254, s53, 56
	s_and_b64 s[18:19], s[52:53], exec
	v_readlane_b32 s37, v251, 57
	v_readlane_b32 s30, v251, 6
	v_readlane_b32 s22, v254, 14
	s_cselect_b32 s14, s37, s31
	v_readlane_b32 s23, v254, 15
	v_writelane_b32 v254, s14, 57
	s_cselect_b32 s14, s36, s30
	v_writelane_b32 v254, s14, 58
	s_and_b64 s[6:7], s[6:7], s[20:21]
	v_writelane_b32 v254, s6, 59
	v_cvt_f32_ubyte0_e32 v0, s54
	v_rcp_iflag_f32_e32 v2, v0
	v_writelane_b32 v254, s7, 60
	v_readlane_b32 s6, v253, 28
	s_or_b32 s6, s25, s6
	v_readlane_b32 s7, v253, 27
	s_mul_i32 s6, s6, s7
	v_readlane_b32 s7, v253, 22
	s_add_i32 s6, s6, s7
	v_readlane_b32 s18, v253, 38
	s_ashr_i32 s7, s6, 31
	v_readlane_b32 s19, v253, 39
	v_mul_f32_e32 v3, v195, v2
	v_writelane_b32 v254, s25, 61
	s_lshr_b32 s7, s7, 29
	v_cndmask_b32_e64 v213, 0, 1, s[4:5]
	s_and_b64 s[4:5], s[4:5], s[18:19]
	v_trunc_f32_e32 v3, v3
	s_add_i32 s7, s6, s7
	v_writelane_b32 v254, s4, 62
	v_fma_f32 v4, -v3, v0, v195
	s_and_b32 s14, s7, -8
	s_ashr_i32 s7, s7, 3
	v_writelane_b32 v254, s5, 63
	v_cmp_ge_f32_e64 s[4:5], |v4|, v0
	v_cvt_u32_f32_e32 v0, v3
	s_lshl_b32 s7, s7, 1
	s_sub_i32 s6, s6, s14
	s_sub_i32 s14, s55, s7
	s_min_i32 s14, s14, 2
	s_cmp_lg_u64 s[4:5], 0
	v_readfirstlane_b32 s4, v0
	v_cvt_f32_ubyte0_e32 v0, s55
	v_mul_f32_e32 v2, 0x4f7ffffe, v2
	v_rcp_iflag_f32_e32 v0, v0
	v_cvt_u32_f32_e32 v2, v2
	s_addc_u32 s4, s4, 0
	s_sub_i32 s5, 0, s54
	v_mul_f32_e32 v0, 0x4f7ffffe, v0
	v_readfirstlane_b32 s15, v2
	v_cvt_u32_f32_e32 v0, v0
	s_mul_i32 s5, s5, s15
	s_mul_hi_u32 s5, s15, s5
	s_add_i32 s5, s15, s5
	v_readfirstlane_b32 s15, v0
	v_writelane_b32 v250, s5, 0
	s_sub_i32 s5, 0, s55
	s_mul_i32 s5, s5, s15
	s_mul_hi_u32 s5, s15, s5
	v_writelane_b32 v250, s55, 1
	s_add_i32 s5, s15, s5
	v_writelane_b32 v250, s5, 2
	s_and_b32 s5, s4, 0xff
	s_add_i32 s5, s5, 64
	v_writelane_b32 v250, s5, 3
	s_sext_i32_i8 s5, s14
	v_cvt_f32_i32_e32 v0, s5
	v_cvt_f32_i32_e32 v2, s6
	s_mul_i32 s4, s4, s54
	v_readlane_b32 s15, v253, 33
	v_rcp_iflag_f32_e32 v3, v0
	s_sub_i32 s4, s15, s4
	v_writelane_b32 v250, s54, 4
	s_and_b32 s4, s4, 0xff
	v_mul_f32_e32 v3, v2, v3
	v_writelane_b32 v250, s4, 5
	s_xor_b32 s4, s6, s5
	v_trunc_f32_e32 v3, v3
	s_ashr_i32 s4, s4, 30
	v_fma_f32 v2, -v3, v0, v2
	s_or_b32 s15, s4, 1
	v_cmp_ge_f32_e64 s[4:5], |v2|, |v0|
	v_cvt_i32_f32_e32 v0, v3
	s_and_b64 s[4:5], s[4:5], exec
	s_cselect_b32 s4, s15, 0
	s_mov_b32 s57, s89
	v_readfirstlane_b32 s5, v0
	s_add_i32 s4, s5, s4
	s_mul_i32 s5, s4, s14
	s_sub_i32 s5, s6, s5
	s_sext_i32_i8 s5, s5
	s_add_i32 s14, s7, s5
	s_sext_i32_i8 s5, s4
	v_writelane_b32 v250, s5, 6
	s_bfe_i64 s[4:5], s[4:5], 0x80000
	s_lshl_b64 s[4:5], s[4:5], 19
	v_writelane_b32 v250, s4, 7
	s_mov_b32 s6, s14
	s_ashr_i32 s15, s14, 31
	v_writelane_b32 v250, s5, 8
	v_writelane_b32 v250, s6, 9
	s_mul_i32 s5, s22, 0x30000
	s_mul_hi_u32 s4, s22, 0x30000
	v_writelane_b32 v250, s7, 10
	s_lshl_b64 s[6:7], s[14:15], 19
	v_writelane_b32 v250, s6, 11
	s_mov_b32 s25, s89
	s_mul_i32 s88, s22, 0x640000
	v_writelane_b32 v250, s7, 12
	s_add_u32 s6, s5, 0x220c000
	v_writelane_b32 v250, s5, 13
	s_addc_u32 s7, s4, 0
	v_writelane_b32 v250, s6, 14
	s_lshl_b32 s1, s1, 1
	s_lshl_b64 s[4:5], s[88:89], 1
	v_writelane_b32 v250, s7, 15
	v_writelane_b32 v250, s56, 16
	v_readlane_b32 s28, v251, 4
	v_readlane_b32 s29, v251, 5
	v_writelane_b32 v250, s57, 17
	v_writelane_b32 v250, s24, 18
	s_mov_b32 s14, s89
	v_readlane_b32 s28, v252, 10
	v_writelane_b32 v250, s25, 19
	v_writelane_b32 v250, s1, 20
	v_writelane_b32 v250, s4, 21
	v_readlane_b32 s30, v252, 12
	s_mov_b64 s[6:7], 0
	v_writelane_b32 v250, s5, 22
	s_mov_b64 s[4:5], -1
	v_writelane_b32 v250, s14, 23
	v_readlane_b32 s29, v252, 11
	v_readlane_b32 s31, v252, 13
	v_readlane_b32 s26, v251, 2
	v_readlane_b32 s27, v251, 3
	v_readlane_b32 s38, v251, 58
	v_readlane_b32 s39, v251, 59
	v_readlane_b32 s40, v251, 60
	v_readlane_b32 s41, v251, 61
	v_readlane_b32 s42, v251, 62
	v_readlane_b32 s43, v251, 63
	v_readlane_b32 s44, v252, 0
	v_readlane_b32 s45, v252, 1
	v_readlane_b32 s46, v252, 2
	v_readlane_b32 s47, v252, 3
	v_readlane_b32 s48, v252, 4
	v_readlane_b32 s49, v252, 5
	v_readlane_b32 s50, v252, 6
	v_readlane_b32 s51, v252, 7
	v_writelane_b32 v250, s15, 24
	s_branch .LBB0_280
.LBB0_278:
	s_or_b64 exec, exec, s[20:21]
	s_waitcnt vmcnt(0)
	buffer_inv sc1
	s_nop 0
	s_nop 0
	s_waitcnt vmcnt(0)

; __device__ __forceinline__ unsigned xb_add(unsigned* p, unsigned v) { return __hip_atomic_fetch_add(p, v, __ATOMIC_RELAXED, __HIP_MEMORY_SCOPE_AGENT); }
; __device__ __forceinline__ void xcd_barrier(const XcdBarrier& b) {
;     ...
;             __builtin_amdgcn_fence(__ATOMIC_ACQUIRE, "agent");
;             xb_add(&bar[XB_XGEN(b.x)], 1u);
;             asm volatile("s_waitcnt vmcnt(0)" ::: "memory");
.LBB0_412:
	s_or_b64 exec, exec, s[22:23]
	s_waitcnt vmcnt(0)
	buffer_inv sc1
	s_nop 0
	s_nop 0
	s_waitcnt vmcnt(0)
